# phase-0 weight conversion software-pipelined (double-buffered sub-item loads) with the wait counting only the current loads, not the previous sub-item's stores
# baseline (speedup 1.0000x reference)
.Lp0_ad0:
	global_load_dword v2, v66, s[4:5] nt
	s_add_u32 s4, s4, s6
	s_addc_u32 s5, s5, 0
	global_load_dword v3, v66, s[4:5] nt
	s_add_u32 s4, s4, s6
	s_addc_u32 s5, s5, 0
	global_load_dword v4, v66, s[4:5] nt
	s_add_u32 s4, s4, s6
	s_addc_u32 s5, s5, 0
	global_load_dword v5, v66, s[4:5] nt
	s_add_u32 s4, s4, s6
	s_addc_u32 s5, s5, 0
	global_load_dword v6, v66, s[4:5] nt
	s_add_u32 s4, s4, s6
	s_addc_u32 s5, s5, 0
	global_load_dword v7, v66, s[4:5] nt
	s_add_u32 s4, s4, s6
	s_addc_u32 s5, s5, 0
	global_load_dword v8, v66, s[4:5] nt
	s_add_u32 s4, s4, s6
	s_addc_u32 s5, s5, 0
	global_load_dword v9, v66, s[4:5] nt
	s_add_u32 s4, s4, s6
	s_addc_u32 s5, s5, 0
	global_load_dword v10, v66, s[4:5] nt
	s_add_u32 s4, s4, s6
	s_addc_u32 s5, s5, 0
	global_load_dword v11, v66, s[4:5] nt
	s_add_u32 s4, s4, s6
	s_addc_u32 s5, s5, 0
	global_load_dword v12, v66, s[4:5] nt
	s_add_u32 s4, s4, s6
	s_addc_u32 s5, s5, 0
	global_load_dword v13, v66, s[4:5] nt
	s_add_u32 s4, s4, s6
	s_addc_u32 s5, s5, 0
	global_load_dword v14, v66, s[4:5] nt
	s_add_u32 s4, s4, s6
	s_addc_u32 s5, s5, 0
	global_load_dword v15, v66, s[4:5] nt
	s_add_u32 s4, s4, s6
	s_addc_u32 s5, s5, 0
	global_load_dword v16, v66, s[4:5] nt
	s_add_u32 s4, s4, s6
	s_addc_u32 s5, s5, 0
	global_load_dword v17, v66, s[4:5] nt
	s_add_u32 s4, s4, s6
	s_addc_u32 s5, s5, 0
	global_load_dword v18, v66, s[4:5] nt
	s_add_u32 s4, s4, s6
	s_addc_u32 s5, s5, 0
	global_load_dword v19, v66, s[4:5] nt
	s_add_u32 s4, s4, s6
	s_addc_u32 s5, s5, 0
	global_load_dword v20, v66, s[4:5] nt
	s_add_u32 s4, s4, s6
	s_addc_u32 s5, s5, 0
	global_load_dword v21, v66, s[4:5] nt
	s_add_u32 s4, s4, s6
	s_addc_u32 s5, s5, 0
	global_load_dword v22, v66, s[4:5] nt
	s_add_u32 s4, s4, s6
	s_addc_u32 s5, s5, 0
	global_load_dword v23, v66, s[4:5] nt
	s_add_u32 s4, s4, s6
	s_addc_u32 s5, s5, 0
	global_load_dword v24, v66, s[4:5] nt
	s_add_u32 s4, s4, s6
	s_addc_u32 s5, s5, 0
	global_load_dword v25, v66, s[4:5] nt
	s_add_u32 s4, s4, s6
	s_addc_u32 s5, s5, 0
	global_load_dword v26, v66, s[4:5] nt
	s_add_u32 s4, s4, s6
	s_addc_u32 s5, s5, 0
	global_load_dword v27, v66, s[4:5] nt
	s_add_u32 s4, s4, s6
	s_addc_u32 s5, s5, 0
	global_load_dword v28, v66, s[4:5] nt
	s_add_u32 s4, s4, s6
	s_addc_u32 s5, s5, 0
	global_load_dword v29, v66, s[4:5] nt
	s_add_u32 s4, s4, s6
	s_addc_u32 s5, s5, 0
	global_load_dword v30, v66, s[4:5] nt
	s_add_u32 s4, s4, s6
	s_addc_u32 s5, s5, 0
	global_load_dword v31, v66, s[4:5] nt
	s_add_u32 s4, s4, s6
	s_addc_u32 s5, s5, 0
	global_load_dword v32, v66, s[4:5] nt
	s_add_u32 s4, s4, s6
	s_addc_u32 s5, s5, 0
	global_load_dword v33, v66, s[4:5] nt
	s_add_u32 s4, s4, s6
	s_addc_u32 s5, s5, 0
	s_add_u32 s1, s1, 1
	s_cmp_eq_u32 s1, 4
	s_cselect_b32 s16, 0x800, 0
	s_cselect_b32 s1, 0, s1
	s_add_u32 s3, s3, s16
	s_cmp_lt_u32 s3, 0x5100
	s_cbranch_scc0 .Lp0_lastA
	s_lshl_b32 s16, s1, 6
	s_cmp_lt_u32 s3, 0x2600
	s_cbranch_scc0 .Lp0_up1
	s_mul_hi_u32 s7, s3, 0x6bca1b
	s_mul_i32 s8, s7, 608
	s_sub_u32 s8, s3, s8
	s_lshl_b32 s9, s7, 8
	s_add_u32 s9, s9, s16
	s_mul_i32 s16, s9, 0x13000
	s_lshl_b32 s17, s8, 7
	s_add_u32 s16, s16, s17
	s_add_u32 s4, s22, s16
	s_addc_u32 s5, s23, 0
	s_mov_b32 s6, 0x26000
	v_mov_b32_e32 v66, v67
	s_lshl_b32 s16, s8, 18
	s_lshl_b32 s17, s9, 1
	s_add_u32 s16, s16, s17
	s_add_u32 s16, s16, 0x1200000
	s_add_u32 s14, s70, s16
	s_addc_u32 s15, s71, 0
	s_branch .Lp0_ad1

.Lp0_ad1:
	global_load_dword v34, v66, s[4:5] nt
	s_add_u32 s4, s4, s6
	s_addc_u32 s5, s5, 0
	global_load_dword v35, v66, s[4:5] nt
	s_add_u32 s4, s4, s6
	s_addc_u32 s5, s5, 0
	global_load_dword v36, v66, s[4:5] nt
	s_add_u32 s4, s4, s6
	s_addc_u32 s5, s5, 0
	global_load_dword v37, v66, s[4:5] nt
	s_add_u32 s4, s4, s6
	s_addc_u32 s5, s5, 0
	global_load_dword v38, v66, s[4:5] nt
	s_add_u32 s4, s4, s6
	s_addc_u32 s5, s5, 0
	global_load_dword v39, v66, s[4:5] nt
	s_add_u32 s4, s4, s6
	s_addc_u32 s5, s5, 0
	global_load_dword v40, v66, s[4:5] nt
	s_add_u32 s4, s4, s6
	s_addc_u32 s5, s5, 0
	global_load_dword v41, v66, s[4:5] nt
	s_add_u32 s4, s4, s6
	s_addc_u32 s5, s5, 0
	global_load_dword v42, v66, s[4:5] nt
	s_add_u32 s4, s4, s6
	s_addc_u32 s5, s5, 0
	global_load_dword v43, v66, s[4:5] nt
	s_add_u32 s4, s4, s6
	s_addc_u32 s5, s5, 0
	global_load_dword v44, v66, s[4:5] nt
	s_add_u32 s4, s4, s6
	s_addc_u32 s5, s5, 0
	global_load_dword v45, v66, s[4:5] nt
	s_add_u32 s4, s4, s6
	s_addc_u32 s5, s5, 0
	global_load_dword v46, v66, s[4:5] nt
	s_add_u32 s4, s4, s6
	s_addc_u32 s5, s5, 0
	global_load_dword v47, v66, s[4:5] nt
	s_add_u32 s4, s4, s6
	s_addc_u32 s5, s5, 0
	global_load_dword v48, v66, s[4:5] nt
	s_add_u32 s4, s4, s6
	s_addc_u32 s5, s5, 0
	global_load_dword v49, v66, s[4:5] nt
	s_add_u32 s4, s4, s6
	s_addc_u32 s5, s5, 0
	global_load_dword v50, v66, s[4:5] nt
	s_add_u32 s4, s4, s6
	s_addc_u32 s5, s5, 0
	global_load_dword v51, v66, s[4:5] nt
	s_add_u32 s4, s4, s6
	s_addc_u32 s5, s5, 0
	global_load_dword v52, v66, s[4:5] nt
	s_add_u32 s4, s4, s6
	s_addc_u32 s5, s5, 0
	global_load_dword v53, v66, s[4:5] nt
	s_add_u32 s4, s4, s6
	s_addc_u32 s5, s5, 0
	global_load_dword v54, v66, s[4:5] nt
	s_add_u32 s4, s4, s6
	s_addc_u32 s5, s5, 0
	global_load_dword v55, v66, s[4:5] nt
	s_add_u32 s4, s4, s6
	s_addc_u32 s5, s5, 0
	global_load_dword v56, v66, s[4:5] nt
	s_add_u32 s4, s4, s6
	s_addc_u32 s5, s5, 0
	global_load_dword v57, v66, s[4:5] nt
	s_add_u32 s4, s4, s6
	s_addc_u32 s5, s5, 0
	global_load_dword v58, v66, s[4:5] nt
	s_add_u32 s4, s4, s6
	s_addc_u32 s5, s5, 0
	global_load_dword v59, v66, s[4:5] nt
	s_add_u32 s4, s4, s6
	s_addc_u32 s5, s5, 0
	global_load_dword v60, v66, s[4:5] nt
	s_add_u32 s4, s4, s6
	s_addc_u32 s5, s5, 0
	global_load_dword v61, v66, s[4:5] nt
	s_add_u32 s4, s4, s6
	s_addc_u32 s5, s5, 0
	global_load_dword v62, v66, s[4:5] nt
	s_add_u32 s4, s4, s6
	s_addc_u32 s5, s5, 0
	global_load_dword v63, v66, s[4:5] nt
	s_add_u32 s4, s4, s6
	s_addc_u32 s5, s5, 0
	global_load_dword v64, v66, s[4:5] nt
	s_add_u32 s4, s4, s6
	s_addc_u32 s5, s5, 0
	global_load_dword v65, v66, s[4:5] nt
	s_add_u32 s4, s4, s6
	s_addc_u32 s5, s5, 0
	s_add_u32 s1, s1, 1
	s_cmp_eq_u32 s1, 4
	s_cselect_b32 s16, 0x800, 0
	s_cselect_b32 s1, 0, s1
	s_add_u32 s3, s3, s16
	s_waitcnt vmcnt(32)
	ds_write2_b32 v71, v2, v3 offset1:66
	ds_write2_b32 v71, v4, v5 offset0:132 offset1:198
	ds_write2_b32 v72, v6, v7 offset1:66
	ds_write2_b32 v72, v8, v9 offset0:132 offset1:198
	ds_write2_b32 v73, v10, v11 offset1:66
	ds_write2_b32 v73, v12, v13 offset0:132 offset1:198
	ds_write2_b32 v74, v14, v15 offset1:66
	ds_write2_b32 v74, v16, v17 offset0:132 offset1:198
	ds_write2_b32 v75, v18, v19 offset1:66
	ds_write2_b32 v75, v20, v21 offset0:132 offset1:198
	ds_write2_b32 v76, v22, v23 offset1:66
	ds_write2_b32 v76, v24, v25 offset0:132 offset1:198
	ds_write2_b32 v77, v26, v27 offset1:66
	ds_write2_b32 v77, v28, v29 offset0:132 offset1:198
	ds_write2_b32 v78, v30, v31 offset1:66
	ds_write2_b32 v78, v32, v33 offset0:132 offset1:198
	s_waitcnt lgkmcnt(0)
	ds_read2_b32 v[88:89], v70 offset0:0 offset1:33
	ds_read2_b32 v[90:91], v70 offset0:66 offset1:99
	ds_read2_b32 v[92:93], v70 offset0:132 offset1:165
	ds_read2_b32 v[94:95], v70 offset0:198 offset1:231
	ds_read2_b32 v[96:97], v70 offset0:8 offset1:41
	ds_read2_b32 v[98:99], v70 offset0:74 offset1:107
	ds_read2_b32 v[100:101], v70 offset0:140 offset1:173
	ds_read2_b32 v[102:103], v70 offset0:206 offset1:239
	ds_read2_b32 v[104:105], v70 offset0:16 offset1:49
	ds_read2_b32 v[106:107], v70 offset0:82 offset1:115
	ds_read2_b32 v[108:109], v70 offset0:148 offset1:181
	ds_read2_b32 v[110:111], v70 offset0:214 offset1:247
	ds_read2_b32 v[112:113], v70 offset0:24 offset1:57
	ds_read2_b32 v[114:115], v70 offset0:90 offset1:123
	ds_read2_b32 v[116:117], v70 offset0:156 offset1:189
	ds_read2_b32 v[118:119], v70 offset0:222 offset1:255
	s_waitcnt lgkmcnt(12)
	v_cvt_pk_bf16_f32 v120, v88, v89
	v_cvt_pk_bf16_f32 v121, v90, v91
	v_cvt_pk_bf16_f32 v122, v92, v93
	v_cvt_pk_bf16_f32 v123, v94, v95
	global_store_dwordx4 v69, v[120:123], s[12:13]
	s_add_u32 s12, s12, 0x10000
	s_addc_u32 s13, s13, 0
	s_waitcnt lgkmcnt(8)
	v_cvt_pk_bf16_f32 v124, v96, v97
	v_cvt_pk_bf16_f32 v125, v98, v99
	v_cvt_pk_bf16_f32 v126, v100, v101
	v_cvt_pk_bf16_f32 v127, v102, v103
	global_store_dwordx4 v69, v[124:127], s[12:13]
	s_add_u32 s12, s12, 0x10000
	s_addc_u32 s13, s13, 0
	s_waitcnt lgkmcnt(4)
	v_cvt_pk_bf16_f32 v120, v104, v105
	v_cvt_pk_bf16_f32 v121, v106, v107
	v_cvt_pk_bf16_f32 v122, v108, v109
	v_cvt_pk_bf16_f32 v123, v110, v111
	global_store_dwordx4 v69, v[120:123], s[12:13]
	s_add_u32 s12, s12, 0x10000
	s_addc_u32 s13, s13, 0
	s_waitcnt lgkmcnt(0)
	v_cvt_pk_bf16_f32 v124, v112, v113
	v_cvt_pk_bf16_f32 v125, v114, v115
	v_cvt_pk_bf16_f32 v126, v116, v117
	v_cvt_pk_bf16_f32 v127, v118, v119
	global_store_dwordx4 v69, v[124:127], s[12:13]
.Lp0_loop:
	s_cmp_lt_u32 s3, 0x5100
	s_cbranch_scc0 .Lp0_lastB
	s_lshl_b32 s16, s1, 6
	s_cmp_lt_u32 s3, 0x2600
	s_cbranch_scc0 .Lp0_up2
	s_mul_hi_u32 s7, s3, 0x6bca1b
	s_mul_i32 s8, s7, 608
	s_sub_u32 s8, s3, s8
	s_lshl_b32 s9, s7, 8
	s_add_u32 s9, s9, s16
	s_mul_i32 s16, s9, 0x13000
	s_lshl_b32 s17, s8, 7
	s_add_u32 s16, s16, s17
	s_add_u32 s4, s22, s16
	s_addc_u32 s5, s23, 0
	s_mov_b32 s6, 0x26000
	v_mov_b32_e32 v66, v67
	s_lshl_b32 s16, s8, 18
	s_lshl_b32 s17, s9, 1
	s_add_u32 s16, s16, s17
	s_add_u32 s16, s16, 0x1200000
	s_add_u32 s12, s70, s16
	s_addc_u32 s13, s71, 0
	s_branch .Lp0_ad2

.Lp0_ad2:
	global_load_dword v2, v66, s[4:5] nt
	s_add_u32 s4, s4, s6
	s_addc_u32 s5, s5, 0
	global_load_dword v3, v66, s[4:5] nt
	s_add_u32 s4, s4, s6
	s_addc_u32 s5, s5, 0
	global_load_dword v4, v66, s[4:5] nt
	s_add_u32 s4, s4, s6
	s_addc_u32 s5, s5, 0
	global_load_dword v5, v66, s[4:5] nt
	s_add_u32 s4, s4, s6
	s_addc_u32 s5, s5, 0
	global_load_dword v6, v66, s[4:5] nt
	s_add_u32 s4, s4, s6
	s_addc_u32 s5, s5, 0
	global_load_dword v7, v66, s[4:5] nt
	s_add_u32 s4, s4, s6
	s_addc_u32 s5, s5, 0
	global_load_dword v8, v66, s[4:5] nt
	s_add_u32 s4, s4, s6
	s_addc_u32 s5, s5, 0
	global_load_dword v9, v66, s[4:5] nt
	s_add_u32 s4, s4, s6
	s_addc_u32 s5, s5, 0
	global_load_dword v10, v66, s[4:5] nt
	s_add_u32 s4, s4, s6
	s_addc_u32 s5, s5, 0
	global_load_dword v11, v66, s[4:5] nt
	s_add_u32 s4, s4, s6
	s_addc_u32 s5, s5, 0
	global_load_dword v12, v66, s[4:5] nt
	s_add_u32 s4, s4, s6
	s_addc_u32 s5, s5, 0
	global_load_dword v13, v66, s[4:5] nt
	s_add_u32 s4, s4, s6
	s_addc_u32 s5, s5, 0
	global_load_dword v14, v66, s[4:5] nt
	s_add_u32 s4, s4, s6
	s_addc_u32 s5, s5, 0
	global_load_dword v15, v66, s[4:5] nt
	s_add_u32 s4, s4, s6
	s_addc_u32 s5, s5, 0
	global_load_dword v16, v66, s[4:5] nt
	s_add_u32 s4, s4, s6
	s_addc_u32 s5, s5, 0
	global_load_dword v17, v66, s[4:5] nt
	s_add_u32 s4, s4, s6
	s_addc_u32 s5, s5, 0
	global_load_dword v18, v66, s[4:5] nt
	s_add_u32 s4, s4, s6
	s_addc_u32 s5, s5, 0
	global_load_dword v19, v66, s[4:5] nt
	s_add_u32 s4, s4, s6
	s_addc_u32 s5, s5, 0
	global_load_dword v20, v66, s[4:5] nt
	s_add_u32 s4, s4, s6
	s_addc_u32 s5, s5, 0
	global_load_dword v21, v66, s[4:5] nt
	s_add_u32 s4, s4, s6
	s_addc_u32 s5, s5, 0
	global_load_dword v22, v66, s[4:5] nt
	s_add_u32 s4, s4, s6
	s_addc_u32 s5, s5, 0
	global_load_dword v23, v66, s[4:5] nt
	s_add_u32 s4, s4, s6
	s_addc_u32 s5, s5, 0
	global_load_dword v24, v66, s[4:5] nt
	s_add_u32 s4, s4, s6
	s_addc_u32 s5, s5, 0
	global_load_dword v25, v66, s[4:5] nt
	s_add_u32 s4, s4, s6
	s_addc_u32 s5, s5, 0
	global_load_dword v26, v66, s[4:5] nt
	s_add_u32 s4, s4, s6
	s_addc_u32 s5, s5, 0
	global_load_dword v27, v66, s[4:5] nt
	s_add_u32 s4, s4, s6
	s_addc_u32 s5, s5, 0
	global_load_dword v28, v66, s[4:5] nt
	s_add_u32 s4, s4, s6
	s_addc_u32 s5, s5, 0
	global_load_dword v29, v66, s[4:5] nt
	s_add_u32 s4, s4, s6
	s_addc_u32 s5, s5, 0
	global_load_dword v30, v66, s[4:5] nt
	s_add_u32 s4, s4, s6
	s_addc_u32 s5, s5, 0
	global_load_dword v31, v66, s[4:5] nt
	s_add_u32 s4, s4, s6
	s_addc_u32 s5, s5, 0
	global_load_dword v32, v66, s[4:5] nt
	s_add_u32 s4, s4, s6
	s_addc_u32 s5, s5, 0
	global_load_dword v33, v66, s[4:5] nt
	s_add_u32 s4, s4, s6
	s_addc_u32 s5, s5, 0
	s_add_u32 s1, s1, 1
	s_cmp_eq_u32 s1, 4
	s_cselect_b32 s16, 0x800, 0
	s_cselect_b32 s1, 0, s1
	s_add_u32 s3, s3, s16
	s_waitcnt vmcnt(36)
	ds_write2_b32 v71, v34, v35 offset1:66
	ds_write2_b32 v71, v36, v37 offset0:132 offset1:198
	ds_write2_b32 v72, v38, v39 offset1:66
	ds_write2_b32 v72, v40, v41 offset0:132 offset1:198
	ds_write2_b32 v73, v42, v43 offset1:66
	ds_write2_b32 v73, v44, v45 offset0:132 offset1:198
	ds_write2_b32 v74, v46, v47 offset1:66
	ds_write2_b32 v74, v48, v49 offset0:132 offset1:198
	ds_write2_b32 v75, v50, v51 offset1:66
	ds_write2_b32 v75, v52, v53 offset0:132 offset1:198
	ds_write2_b32 v76, v54, v55 offset1:66
	ds_write2_b32 v76, v56, v57 offset0:132 offset1:198
	ds_write2_b32 v77, v58, v59 offset1:66
	ds_write2_b32 v77, v60, v61 offset0:132 offset1:198
	ds_write2_b32 v78, v62, v63 offset1:66
	ds_write2_b32 v78, v64, v65 offset0:132 offset1:198
	s_waitcnt lgkmcnt(0)
	ds_read2_b32 v[88:89], v70 offset0:0 offset1:33
	ds_read2_b32 v[90:91], v70 offset0:66 offset1:99
	ds_read2_b32 v[92:93], v70 offset0:132 offset1:165
	ds_read2_b32 v[94:95], v70 offset0:198 offset1:231
	ds_read2_b32 v[96:97], v70 offset0:8 offset1:41
	ds_read2_b32 v[98:99], v70 offset0:74 offset1:107
	ds_read2_b32 v[100:101], v70 offset0:140 offset1:173
	ds_read2_b32 v[102:103], v70 offset0:206 offset1:239
	ds_read2_b32 v[104:105], v70 offset0:16 offset1:49
	ds_read2_b32 v[106:107], v70 offset0:82 offset1:115
	ds_read2_b32 v[108:109], v70 offset0:148 offset1:181
	ds_read2_b32 v[110:111], v70 offset0:214 offset1:247
	ds_read2_b32 v[112:113], v70 offset0:24 offset1:57
	ds_read2_b32 v[114:115], v70 offset0:90 offset1:123
	ds_read2_b32 v[116:117], v70 offset0:156 offset1:189
	ds_read2_b32 v[118:119], v70 offset0:222 offset1:255
	s_waitcnt lgkmcnt(12)
	v_cvt_pk_bf16_f32 v120, v88, v89
	v_cvt_pk_bf16_f32 v121, v90, v91
	v_cvt_pk_bf16_f32 v122, v92, v93
	v_cvt_pk_bf16_f32 v123, v94, v95
	global_store_dwordx4 v69, v[120:123], s[14:15]
	s_add_u32 s14, s14, 0x10000
	s_addc_u32 s15, s15, 0
	s_waitcnt lgkmcnt(8)
	v_cvt_pk_bf16_f32 v124, v96, v97
	v_cvt_pk_bf16_f32 v125, v98, v99
	v_cvt_pk_bf16_f32 v126, v100, v101
	v_cvt_pk_bf16_f32 v127, v102, v103
	global_store_dwordx4 v69, v[124:127], s[14:15]
	s_add_u32 s14, s14, 0x10000
	s_addc_u32 s15, s15, 0
	s_waitcnt lgkmcnt(4)
	v_cvt_pk_bf16_f32 v120, v104, v105
	v_cvt_pk_bf16_f32 v121, v106, v107
	v_cvt_pk_bf16_f32 v122, v108, v109
	v_cvt_pk_bf16_f32 v123, v110, v111
	global_store_dwordx4 v69, v[120:123], s[14:15]
	s_add_u32 s14, s14, 0x10000
	s_addc_u32 s15, s15, 0
	s_waitcnt lgkmcnt(0)
	v_cvt_pk_bf16_f32 v124, v112, v113
	v_cvt_pk_bf16_f32 v125, v114, v115
	v_cvt_pk_bf16_f32 v126, v116, v117
	v_cvt_pk_bf16_f32 v127, v118, v119
	global_store_dwordx4 v69, v[124:127], s[14:15]
	s_cmp_lt_u32 s3, 0x5100
	s_cbranch_scc0 .Lp0_lastA
	s_lshl_b32 s16, s1, 6
	s_cmp_lt_u32 s3, 0x2600
	s_cbranch_scc0 .Lp0_up3
	s_mul_hi_u32 s7, s3, 0x6bca1b
	s_mul_i32 s8, s7, 608
	s_sub_u32 s8, s3, s8
	s_lshl_b32 s9, s7, 8
	s_add_u32 s9, s9, s16
	s_mul_i32 s16, s9, 0x13000
	s_lshl_b32 s17, s8, 7
	s_add_u32 s16, s16, s17
	s_add_u32 s4, s22, s16
	s_addc_u32 s5, s23, 0
	s_mov_b32 s6, 0x26000
	v_mov_b32_e32 v66, v67
	s_lshl_b32 s16, s8, 18
	s_lshl_b32 s17, s9, 1
	s_add_u32 s16, s16, s17
	s_add_u32 s16, s16, 0x1200000
	s_add_u32 s14, s70, s16
	s_addc_u32 s15, s71, 0
	s_branch .Lp0_ad3

.Lp0_ad3:
	global_load_dword v34, v66, s[4:5] nt
	s_add_u32 s4, s4, s6
	s_addc_u32 s5, s5, 0
	global_load_dword v35, v66, s[4:5] nt
	s_add_u32 s4, s4, s6
	s_addc_u32 s5, s5, 0
	global_load_dword v36, v66, s[4:5] nt
	s_add_u32 s4, s4, s6
	s_addc_u32 s5, s5, 0
	global_load_dword v37, v66, s[4:5] nt
	s_add_u32 s4, s4, s6
	s_addc_u32 s5, s5, 0
	global_load_dword v38, v66, s[4:5] nt
	s_add_u32 s4, s4, s6
	s_addc_u32 s5, s5, 0
	global_load_dword v39, v66, s[4:5] nt
	s_add_u32 s4, s4, s6
	s_addc_u32 s5, s5, 0
	global_load_dword v40, v66, s[4:5] nt
	s_add_u32 s4, s4, s6
	s_addc_u32 s5, s5, 0
	global_load_dword v41, v66, s[4:5] nt
	s_add_u32 s4, s4, s6
	s_addc_u32 s5, s5, 0
	global_load_dword v42, v66, s[4:5] nt
	s_add_u32 s4, s4, s6
	s_addc_u32 s5, s5, 0
	global_load_dword v43, v66, s[4:5] nt
	s_add_u32 s4, s4, s6
	s_addc_u32 s5, s5, 0
	global_load_dword v44, v66, s[4:5] nt
	s_add_u32 s4, s4, s6
	s_addc_u32 s5, s5, 0
	global_load_dword v45, v66, s[4:5] nt
	s_add_u32 s4, s4, s6
	s_addc_u32 s5, s5, 0
	global_load_dword v46, v66, s[4:5] nt
	s_add_u32 s4, s4, s6
	s_addc_u32 s5, s5, 0
	global_load_dword v47, v66, s[4:5] nt
	s_add_u32 s4, s4, s6
	s_addc_u32 s5, s5, 0
	global_load_dword v48, v66, s[4:5] nt
	s_add_u32 s4, s4, s6
	s_addc_u32 s5, s5, 0
	global_load_dword v49, v66, s[4:5] nt
	s_add_u32 s4, s4, s6
	s_addc_u32 s5, s5, 0
	global_load_dword v50, v66, s[4:5] nt
	s_add_u32 s4, s4, s6
	s_addc_u32 s5, s5, 0
	global_load_dword v51, v66, s[4:5] nt
	s_add_u32 s4, s4, s6
	s_addc_u32 s5, s5, 0
	global_load_dword v52, v66, s[4:5] nt
	s_add_u32 s4, s4, s6
	s_addc_u32 s5, s5, 0
	global_load_dword v53, v66, s[4:5] nt
	s_add_u32 s4, s4, s6
	s_addc_u32 s5, s5, 0
	global_load_dword v54, v66, s[4:5] nt
	s_add_u32 s4, s4, s6
	s_addc_u32 s5, s5, 0
	global_load_dword v55, v66, s[4:5] nt
	s_add_u32 s4, s4, s6
	s_addc_u32 s5, s5, 0
	global_load_dword v56, v66, s[4:5] nt
	s_add_u32 s4, s4, s6
	s_addc_u32 s5, s5, 0
	global_load_dword v57, v66, s[4:5] nt
	s_add_u32 s4, s4, s6
	s_addc_u32 s5, s5, 0
	global_load_dword v58, v66, s[4:5] nt
	s_add_u32 s4, s4, s6
	s_addc_u32 s5, s5, 0
	global_load_dword v59, v66, s[4:5] nt
	s_add_u32 s4, s4, s6
	s_addc_u32 s5, s5, 0
	global_load_dword v60, v66, s[4:5] nt
	s_add_u32 s4, s4, s6
	s_addc_u32 s5, s5, 0
	global_load_dword v61, v66, s[4:5] nt
	s_add_u32 s4, s4, s6
	s_addc_u32 s5, s5, 0
	global_load_dword v62, v66, s[4:5] nt
	s_add_u32 s4, s4, s6
	s_addc_u32 s5, s5, 0
	global_load_dword v63, v66, s[4:5] nt
	s_add_u32 s4, s4, s6
	s_addc_u32 s5, s5, 0
	global_load_dword v64, v66, s[4:5] nt
	s_add_u32 s4, s4, s6
	s_addc_u32 s5, s5, 0
	global_load_dword v65, v66, s[4:5] nt
	s_add_u32 s4, s4, s6
	s_addc_u32 s5, s5, 0
	s_add_u32 s1, s1, 1
	s_cmp_eq_u32 s1, 4
	s_cselect_b32 s16, 0x800, 0
	s_cselect_b32 s1, 0, s1
	s_add_u32 s3, s3, s16
	s_waitcnt vmcnt(36)
	ds_write2_b32 v71, v2, v3 offset1:66
	ds_write2_b32 v71, v4, v5 offset0:132 offset1:198
	ds_write2_b32 v72, v6, v7 offset1:66
	ds_write2_b32 v72, v8, v9 offset0:132 offset1:198
	ds_write2_b32 v73, v10, v11 offset1:66
	ds_write2_b32 v73, v12, v13 offset0:132 offset1:198
	ds_write2_b32 v74, v14, v15 offset1:66
	ds_write2_b32 v74, v16, v17 offset0:132 offset1:198
	ds_write2_b32 v75, v18, v19 offset1:66
	ds_write2_b32 v75, v20, v21 offset0:132 offset1:198
	ds_write2_b32 v76, v22, v23 offset1:66
	ds_write2_b32 v76, v24, v25 offset0:132 offset1:198
	ds_write2_b32 v77, v26, v27 offset1:66
	ds_write2_b32 v77, v28, v29 offset0:132 offset1:198
	ds_write2_b32 v78, v30, v31 offset1:66
	ds_write2_b32 v78, v32, v33 offset0:132 offset1:198
	s_waitcnt lgkmcnt(0)
	ds_read2_b32 v[88:89], v70 offset0:0 offset1:33
	ds_read2_b32 v[90:91], v70 offset0:66 offset1:99
	ds_read2_b32 v[92:93], v70 offset0:132 offset1:165
	ds_read2_b32 v[94:95], v70 offset0:198 offset1:231
	ds_read2_b32 v[96:97], v70 offset0:8 offset1:41
	ds_read2_b32 v[98:99], v70 offset0:74 offset1:107
	ds_read2_b32 v[100:101], v70 offset0:140 offset1:173
	ds_read2_b32 v[102:103], v70 offset0:206 offset1:239
	ds_read2_b32 v[104:105], v70 offset0:16 offset1:49
	ds_read2_b32 v[106:107], v70 offset0:82 offset1:115
	ds_read2_b32 v[108:109], v70 offset0:148 offset1:181
	ds_read2_b32 v[110:111], v70 offset0:214 offset1:247
	ds_read2_b32 v[112:113], v70 offset0:24 offset1:57
	ds_read2_b32 v[114:115], v70 offset0:90 offset1:123
	ds_read2_b32 v[116:117], v70 offset0:156 offset1:189
	ds_read2_b32 v[118:119], v70 offset0:222 offset1:255
	s_waitcnt lgkmcnt(12)
	v_cvt_pk_bf16_f32 v120, v88, v89
	v_cvt_pk_bf16_f32 v121, v90, v91
	v_cvt_pk_bf16_f32 v122, v92, v93
	v_cvt_pk_bf16_f32 v123, v94, v95
	global_store_dwordx4 v69, v[120:123], s[12:13]
	s_add_u32 s12, s12, 0x10000
	s_addc_u32 s13, s13, 0
	s_waitcnt lgkmcnt(8)
	v_cvt_pk_bf16_f32 v124, v96, v97
	v_cvt_pk_bf16_f32 v125, v98, v99
	v_cvt_pk_bf16_f32 v126, v100, v101
	v_cvt_pk_bf16_f32 v127, v102, v103
	global_store_dwordx4 v69, v[124:127], s[12:13]
	s_add_u32 s12, s12, 0x10000
	s_addc_u32 s13, s13, 0
	s_waitcnt lgkmcnt(4)
	v_cvt_pk_bf16_f32 v120, v104, v105
	v_cvt_pk_bf16_f32 v121, v106, v107
	v_cvt_pk_bf16_f32 v122, v108, v109
	v_cvt_pk_bf16_f32 v123, v110, v111
	global_store_dwordx4 v69, v[120:123], s[12:13]
	s_add_u32 s12, s12, 0x10000
	s_addc_u32 s13, s13, 0
	s_waitcnt lgkmcnt(0)
	v_cvt_pk_bf16_f32 v124, v112, v113
	v_cvt_pk_bf16_f32 v125, v114, v115
	v_cvt_pk_bf16_f32 v126, v116, v117
	v_cvt_pk_bf16_f32 v127, v118, v119
	global_store_dwordx4 v69, v[124:127], s[12:13]
	s_branch .Lp0_loop
